# mLSTM phases: seg_scan ladder replaced by batched loads + register recurrence + batched stores; both seg_pass chunk loops issue their global loads before the chunk barrier (wave-0 scalar loads issued
# speedup vs baseline: 1.0058x; 1.0047x over previous
.LBB0_1053:
	s_add_i32 s0, s60, s59
	s_lshl_b32 s22, s0, 6
	s_lshl_b64 s[24:25], s[0:1], 2
	s_add_u32 s26, s13, s24
	s_mov_b32 s23, s1
	v_add_u32_e32 v118, s22, v93
	v_add_u32_e32 v120, s22, v94
	s_addc_u32 s27, s58, s25
	s_lshl_b64 s[24:25], s[22:23], 2
	v_ashrrev_i32_e32 v119, 31, v118
	v_ashrrev_i32_e32 v121, 31, v120
	v_or_b32_e32 v64, s22, v72
	s_add_u32 s24, s14, s24
	v_lshlrev_b64 v[118:119], 8, v[118:119]
	v_lshlrev_b64 v[120:121], 8, v[120:121]
	v_lshlrev_b64 v[126:127], 9, v[64:65]
	v_lshlrev_b64 v[134:135], 2, v[64:65]
	s_addc_u32 s25, s15, s25
	s_waitcnt lgkmcnt(0)
	global_load_dwordx2 v[74:75], v65, s[26:27]
	global_load_dword v116, v65, s[24:25] offset:252
	v_lshl_add_u64 v[118:119], v[68:69], 0, v[118:119]
	v_lshl_add_u64 v[122:123], v[68:69], 0, v[120:121]
	v_lshl_add_u64 v[126:127], v[70:71], 0, v[126:127]
	v_lshl_add_u64 v[128:129], s[14:15], 0, v[134:135]
	v_or_b32_e32 v64, s22, v95
	global_load_dwordx4 v[118:121], v[118:119], off
	s_nop 0
	global_load_dwordx4 v[122:125], v[122:123], off
	s_nop 0
	global_load_dword v117, v[128:129], off
	s_nop 0
	global_load_dwordx4 v[126:129], v[126:127], off
	v_lshlrev_b64 v[130:131], 9, v[64:65]
	v_lshl_add_u64 v[130:131], v[70:71], 0, v[130:131]
	global_load_dword v142, v112, s[24:25] offset:64
	s_nop 0
	global_load_dwordx4 v[130:133], v[130:131], off
	v_lshl_add_u64 v[138:139], s[18:19], 0, v[134:135]
	global_load_dword v143, v112, s[24:25] offset:128
	global_load_dword v144, v[138:139], off
	global_load_dword v145, v[138:139], off offset:64
	global_load_dword v146, v[138:139], off offset:128
	v_or_b32_e32 v64, s22, v96
	v_lshlrev_b64 v[134:135], 9, v[64:65]
	v_lshl_add_u64 v[134:135], v[70:71], 0, v[134:135]
	global_load_dwordx4 v[134:137], v[134:135], off
	s_nop 0
	global_load_dword v147, v112, s[24:25] offset:192
	global_load_dword v148, v[138:139], off offset:192
	v_or_b32_e32 v64, s22, v97
	v_lshlrev_b64 v[138:139], 9, v[64:65]
	v_lshl_add_u64 v[138:139], v[70:71], 0, v[138:139]
	global_load_dwordx4 v[138:141], v[138:139], off
	s_and_saveexec_b64 s[26:27], s[4:5]
	s_cbranch_execz .Lmy_ml10_nol
	v_add_u32_e32 v152, s22, v66
	v_ashrrev_i32_e32 v153, 31, v152
	v_lshl_add_u64 v[154:155], v[66:67], 2, s[24:25]
	global_load_dword v149, v[154:155], off
	v_lshlrev_b64 v[152:153], 2, v[152:153]
	v_lshl_add_u64 v[154:155], s[18:19], 0, v[152:153]
	v_lshl_add_u64 v[152:153], s[10:11], 0, v[152:153]
	global_load_dword v150, v[154:155], off
	s_nop 0
	global_load_dword v151, v[152:153], off
.Lmy_ml10_nol:
	s_or_b64 exec, exec, s[26:27]
	s_barrier
	s_waitcnt vmcnt(13)
	ds_write_b128 v109, v[118:121] offset:16384
	s_waitcnt vmcnt(12)
	ds_write_b128 v110, v[122:125] offset:16384
	s_waitcnt vmcnt(11)
	v_sub_f32_e32 v64, v116, v117
	s_waitcnt vmcnt(10)
	v_lshlrev_b32_e32 v118, 16, v126
	s_waitcnt vmcnt(9)
	v_sub_f32_e32 v117, v116, v142
	s_waitcnt vmcnt(6)
	v_add_f32_e32 v64, v64, v144
	v_sub_f32_e32 v64, v64, v75
	v_mul_f32_e32 v64, 0x3fb8aa3b, v64
	v_exp_f32_e32 v64, v64
	v_and_b32_e32 v119, 0xffff0000, v126
	v_lshlrev_b32_e32 v120, 16, v127
	v_and_b32_e32 v121, 0xffff0000, v127
	v_lshlrev_b32_e32 v122, 16, v128
	v_and_b32_e32 v123, 0xffff0000, v128
	v_lshlrev_b32_e32 v124, 16, v129
	v_and_b32_e32 v125, 0xffff0000, v129
	v_sub_f32_e32 v143, v116, v143
	s_waitcnt vmcnt(5)
	v_add_f32_e32 v117, v117, v145
	v_sub_f32_e32 v117, v117, v75
	v_pk_mul_f32 v[118:119], v[64:65], v[118:119] op_sel_hi:[0,1]
	v_pk_mul_f32 v[120:121], v[64:65], v[120:121] op_sel_hi:[0,1]
	v_pk_mul_f32 v[122:123], v[64:65], v[122:123] op_sel_hi:[0,1]
	v_pk_mul_f32 v[124:125], v[64:65], v[124:125] op_sel_hi:[0,1]
	s_waitcnt vmcnt(4)
	v_add_f32_e32 v64, v143, v146
	v_mul_f32_e32 v117, 0x3fb8aa3b, v117
	v_sub_f32_e32 v64, v64, v75
	v_exp_f32_e32 v142, v117
	v_mul_f32_e32 v64, 0x3fb8aa3b, v64
	v_exp_f32_e32 v64, v64
	v_lshlrev_b32_e32 v126, 16, v130
	v_and_b32_e32 v127, 0xffff0000, v130
	v_lshlrev_b32_e32 v128, 16, v131
	v_and_b32_e32 v129, 0xffff0000, v131
	v_lshlrev_b32_e32 v130, 16, v132
	v_and_b32_e32 v131, 0xffff0000, v132
	v_lshlrev_b32_e32 v132, 16, v133
	v_and_b32_e32 v133, 0xffff0000, v133
	v_cvt_pk_bf16_f32 v118, v118, v119
	v_cvt_pk_bf16_f32 v119, v120, v121
	v_cvt_pk_bf16_f32 v120, v122, v123
	v_cvt_pk_bf16_f32 v121, v124, v125
	v_pk_mul_f32 v[126:127], v[142:143], v[126:127] op_sel_hi:[0,1]
	v_pk_mul_f32 v[128:129], v[142:143], v[128:129] op_sel_hi:[0,1]
	v_pk_mul_f32 v[130:131], v[142:143], v[130:131] op_sel_hi:[0,1]
	v_pk_mul_f32 v[132:133], v[142:143], v[132:133] op_sel_hi:[0,1]
	ds_write_b128 v111, v[118:121]
	s_waitcnt vmcnt(3)
	v_lshlrev_b32_e32 v118, 16, v134
	v_and_b32_e32 v119, 0xffff0000, v134
	v_lshlrev_b32_e32 v120, 16, v135
	v_and_b32_e32 v121, 0xffff0000, v135
	v_cvt_pk_bf16_f32 v122, v126, v127
	v_cvt_pk_bf16_f32 v123, v128, v129
	v_cvt_pk_bf16_f32 v124, v130, v131
	v_cvt_pk_bf16_f32 v125, v132, v133
	v_pk_mul_f32 v[118:119], v[64:65], v[118:119] op_sel_hi:[0,1]
	v_pk_mul_f32 v[120:121], v[64:65], v[120:121] op_sel_hi:[0,1]
	ds_write_b128 v113, v[122:125]
	v_cvt_pk_bf16_f32 v118, v118, v119
	v_cvt_pk_bf16_f32 v119, v120, v121
	v_lshlrev_b32_e32 v120, 16, v136
	v_and_b32_e32 v121, 0xffff0000, v136
	v_lshlrev_b32_e32 v122, 16, v137
	v_and_b32_e32 v123, 0xffff0000, v137
	v_pk_mul_f32 v[120:121], v[64:65], v[120:121] op_sel_hi:[0,1]
	v_pk_mul_f32 v[122:123], v[64:65], v[122:123] op_sel_hi:[0,1]
	s_waitcnt vmcnt(2)
	v_sub_f32_e32 v64, v116, v147
	s_waitcnt vmcnt(1)
	v_add_f32_e32 v64, v64, v148
	v_sub_f32_e32 v64, v64, v75
	v_mul_f32_e32 v64, 0x3fb8aa3b, v64
	v_exp_f32_e32 v64, v64
	v_cvt_pk_bf16_f32 v120, v120, v121
	v_cvt_pk_bf16_f32 v121, v122, v123
	ds_write_b128 v114, v[118:121]
	s_waitcnt vmcnt(0)
	v_lshlrev_b32_e32 v118, 16, v138
	v_and_b32_e32 v119, 0xffff0000, v138
	v_lshlrev_b32_e32 v120, 16, v139
	v_and_b32_e32 v121, 0xffff0000, v139
	v_pk_mul_f32 v[118:119], v[64:65], v[118:119] op_sel_hi:[0,1]
	v_pk_mul_f32 v[120:121], v[64:65], v[120:121] op_sel_hi:[0,1]
	v_cvt_pk_bf16_f32 v118, v118, v119
	v_cvt_pk_bf16_f32 v119, v120, v121
	v_lshlrev_b32_e32 v120, 16, v140
	v_and_b32_e32 v121, 0xffff0000, v140
	v_lshlrev_b32_e32 v122, 16, v141
	v_and_b32_e32 v123, 0xffff0000, v141
	v_pk_mul_f32 v[120:121], v[64:65], v[120:121] op_sel_hi:[0,1]
	v_pk_mul_f32 v[122:123], v[64:65], v[122:123] op_sel_hi:[0,1]
	v_cvt_pk_bf16_f32 v120, v120, v121
	v_cvt_pk_bf16_f32 v121, v122, v123
	ds_write_b128 v115, v[118:121]
	s_and_saveexec_b64 s[26:27], s[4:5]
	s_cbranch_execz .LBB0_1055
	v_max_f32_e32 v119, v74, v74
	v_sub_f32_e32 v120, v116, v149
	ds_write_b32 v87, v149
	ds_write_b32 v88, v150
	v_add_f32_e32 v117, v120, v150
	v_sub_f32_e32 v117, v117, v75
	v_mul_f32_e32 v117, 0x3fb8aa3b, v117
	v_max_f32_e32 v118, v151, v151
	v_exp_f32_e32 v117, v117
	v_max_f32_e32 v118, v119, v118
	v_add_f32_e32 v64, v149, v118
	ds_write_b32 v89, v64
	ds_write_b32 v90, v117

.LBB0_1121:
	s_or_b64 exec, exec, s[8:9]
	v_lshlrev_b32_e32 v4, 4, v4
	v_lshlrev_b32_e32 v0, 2, v8
	v_ashrrev_i32_e32 v5, 31, v4
	v_add_u32_e32 v10, s16, v10
	v_lshl_add_u64 v[144:145], v[4:5], 2, s[48:49]
	v_add_co_u32_e32 v144, vcc, 0x184000, v144
	s_nop 1
	v_addc_co_u32_e32 v145, vcc, 0, v145, vcc
	v_cmp_lt_i32_e32 vcc, s13, v10
	s_or_b64 s[4:5], vcc, s[4:5]
	v_mov_b64_e32 v[80:81], v[2:3]
	v_lshl_add_u64 v[82:83], v[80:81], 0, v[0:1]
	v_lshl_add_u64 v[84:85], v[82:83], 0, v[0:1]
	v_lshl_add_u64 v[86:87], v[84:85], 0, v[0:1]
	v_lshl_add_u64 v[88:89], v[86:87], 0, v[0:1]
	v_lshl_add_u64 v[90:91], v[88:89], 0, v[0:1]
	v_lshl_add_u64 v[92:93], v[90:91], 0, v[0:1]
	v_lshl_add_u64 v[94:95], v[92:93], 0, v[0:1]
	v_lshl_add_u64 v[96:97], v[94:95], 0, v[0:1]
	v_lshl_add_u64 v[98:99], v[96:97], 0, v[0:1]
	v_lshl_add_u64 v[100:101], v[98:99], 0, v[0:1]
	v_lshl_add_u64 v[102:103], v[100:101], 0, v[0:1]
	v_lshl_add_u64 v[104:105], v[102:103], 0, v[0:1]
	v_lshl_add_u64 v[106:107], v[104:105], 0, v[0:1]
	v_lshl_add_u64 v[108:109], v[106:107], 0, v[0:1]
	v_lshl_add_u64 v[110:111], v[108:109], 0, v[0:1]
	global_load_dword v112, v[80:81], off
	global_load_dword v113, v[82:83], off
	global_load_dword v114, v[84:85], off
	global_load_dword v115, v[86:87], off
	global_load_dword v116, v[88:89], off
	global_load_dword v117, v[90:91], off
	global_load_dword v118, v[92:93], off
	global_load_dword v119, v[94:95], off
	global_load_dword v120, v[96:97], off
	global_load_dword v121, v[98:99], off
	global_load_dword v122, v[100:101], off
	global_load_dword v123, v[102:103], off
	global_load_dword v124, v[104:105], off
	global_load_dword v125, v[106:107], off
	global_load_dword v126, v[108:109], off
	global_load_dword v128, v[144:145], off
	global_load_dword v129, v[144:145], off offset:4
	global_load_dword v130, v[144:145], off offset:8
	global_load_dword v131, v[144:145], off offset:12
	global_load_dword v132, v[144:145], off offset:16
	global_load_dword v133, v[144:145], off offset:20
	global_load_dword v134, v[144:145], off offset:24
	global_load_dword v135, v[144:145], off offset:28
	global_load_dword v136, v[144:145], off offset:32
	global_load_dword v137, v[144:145], off offset:36
	global_load_dword v138, v[144:145], off offset:40
	global_load_dword v139, v[144:145], off offset:44
	global_load_dword v140, v[144:145], off offset:48
	global_load_dword v141, v[144:145], off offset:52
	global_load_dword v142, v[144:145], off offset:56
	global_store_dword v[80:81], v1, off
	s_waitcnt vmcnt(1)
	v_fmac_f32_e32 v112, 0, v128
	v_fmac_f32_e32 v113, v112, v129
	v_fmac_f32_e32 v114, v113, v130
	v_fmac_f32_e32 v115, v114, v131
	v_fmac_f32_e32 v116, v115, v132
	v_fmac_f32_e32 v117, v116, v133
	v_fmac_f32_e32 v118, v117, v134
	v_fmac_f32_e32 v119, v118, v135
	v_fmac_f32_e32 v120, v119, v136
	v_fmac_f32_e32 v121, v120, v137
	v_fmac_f32_e32 v122, v121, v138
	v_fmac_f32_e32 v123, v122, v139
	v_fmac_f32_e32 v124, v123, v140
	v_fmac_f32_e32 v125, v124, v141
	v_fmac_f32_e32 v126, v125, v142
	global_store_dword v[82:83], v112, off
	global_store_dword v[84:85], v113, off
	global_store_dword v[86:87], v114, off
	global_store_dword v[88:89], v115, off
	global_store_dword v[90:91], v116, off
	global_store_dword v[92:93], v117, off
	global_store_dword v[94:95], v118, off
	global_store_dword v[96:97], v119, off
	global_store_dword v[98:99], v120, off
	global_store_dword v[100:101], v121, off
	global_store_dword v[102:103], v122, off
	global_store_dword v[104:105], v123, off
	global_store_dword v[106:107], v124, off
	global_store_dword v[108:109], v125, off
	global_store_dword v[110:111], v126, off
	s_andn2_b64 exec, exec, s[4:5]
	s_cbranch_execz .LBB0_1126

.LBB0_1189:
	s_add_i32 s56, s47, s63
	s_lshl_b32 s44, s56, 6
	s_lshl_b64 s[74:75], s[56:57], 2
	s_add_u32 s74, s61, s74
	s_addc_u32 s75, s62, s75
	s_mov_b32 s45, s57
	global_load_dwordx2 v[134:135], v113, s[74:75]
	s_lshl_b64 s[74:75], s[44:45], 2
	s_add_u32 s74, s66, s74
	s_addc_u32 s75, s67, s75
	global_load_dword v229, v113, s[74:75] offset:252
	v_add_u32_e32 v64, s44, v167
	v_ashrrev_i32_e32 v65, 31, v64
	v_lshlrev_b64 v[68:69], 8, v[64:65]
	v_lshl_add_u64 v[64:65], v[116:117], 0, v[68:69]
	global_load_dwordx4 v[80:83], v[64:65], off
	v_lshl_add_u64 v[64:65], v[118:119], 0, v[68:69]
	global_load_dwordx4 v[84:87], v[64:65], off
	v_add_u32_e32 v64, s44, v168
	v_ashrrev_i32_e32 v65, 31, v64
	v_lshlrev_b64 v[68:69], 8, v[64:65]
	v_lshl_add_u64 v[64:65], v[116:117], 0, v[68:69]
	global_load_dwordx4 v[88:91], v[64:65], off
	v_lshl_add_u64 v[64:65], v[118:119], 0, v[68:69]
	global_load_dwordx4 v[92:95], v[64:65], off
	v_or_b32_e32 v112, s44, v132
	v_lshlrev_b32_e32 v78, 2, v132
	v_lshlrev_b64 v[68:69], 2, v[112:113]
	v_lshl_add_u64 v[70:71], s[66:67], 0, v[68:69]
	v_lshl_add_u64 v[68:69], s[68:69], 0, v[68:69]
	global_load_dword v231, v[68:69], off
	global_load_dword v230, v[70:71], off
	v_lshlrev_b64 v[64:65], 9, v[112:113]
	v_lshl_add_u64 v[64:65], v[120:121], 0, v[64:65]
	global_load_dwordx4 v[96:99], v[64:65], off
	v_or_b32_e32 v112, s44, v170
	v_lshlrev_b64 v[64:65], 9, v[112:113]
	v_lshl_add_u64 v[64:65], v[120:121], 0, v[64:65]
	global_load_dwordx4 v[100:103], v[64:65], off
	global_load_dword v232, v78, s[74:75] offset:64
	v_add_u32_e32 v112, s44, v132
	v_lshl_add_u64 v[68:69], v[112:113], 2, s[68:69]
	global_load_dword v233, v[68:69], off offset:64
	v_or_b32_e32 v112, s44, v172
	v_lshlrev_b64 v[64:65], 9, v[112:113]
	v_lshl_add_u64 v[64:65], v[120:121], 0, v[64:65]
	global_load_dwordx4 v[104:107], v[64:65], off
	global_load_dword v234, v78, s[74:75] offset:128
	global_load_dword v235, v[68:69], off offset:128
	v_or_b32_e32 v112, s44, v174
	v_lshlrev_b64 v[64:65], 9, v[112:113]
	v_lshl_add_u64 v[64:65], v[120:121], 0, v[64:65]
	global_load_dwordx4 v[108:111], v[64:65], off
	global_load_dword v236, v78, s[74:75] offset:192
	global_load_dword v237, v[68:69], off offset:192
	s_and_saveexec_b64 s[92:93], s[2:3]
	s_cbranch_execz .Lmy_ml_nol
	v_add_u32_e32 v64, s44, v114
	v_ashrrev_i32_e32 v65, 31, v64
	v_lshl_add_u64 v[66:67], v[114:115], 2, s[74:75]
	v_lshlrev_b64 v[64:65], 2, v[64:65]
	global_load_dword v238, v[66:67], off
	v_lshl_add_u64 v[66:67], s[68:69], 0, v[64:65]
	global_load_dword v239, v[66:67], off
	v_lshl_add_u64 v[64:65], s[64:65], 0, v[64:65]
	global_load_dword v240, v[64:65], off
.Lmy_ml_nol:
	s_or_b64 exec, exec, s[92:93]
	s_cmp_eq_u32 s47, 0
	s_waitcnt lgkmcnt(0)
	s_barrier
	s_cbranch_scc1 .Lmy_ml12_c0
	s_lshl_b32 s45, s56, 18
	s_add_u32 s45, s96, s45
	s_addc_u32 s56, s88, 0
	s_lshl_b32 s92, s46, 1
	s_add_u32 s92, s45, s92
	s_addc_u32 s93, s56, 0
	v_lshlrev_b32_e32 v112, 1, v128
	v_lshl_add_u64 v[64:65], s[92:93], 0, v[112:113]
	s_mov_b32 s92, 0xfffc0000
	s_mov_b32 s93, -1
	v_lshl_add_u64 v[68:69], v[64:65], 0, s[92:93]
	v_add_u32_e32 v64, v145, v149
	ds_read2_b64 v[64:67], v64 offset1:1
	v_lshl_add_u64 v[70:71], v[68:69], 0, v[122:123]
	s_waitcnt lgkmcnt(0)
	global_store_dwordx4 v[70:71], v[64:67], off
	s_nop 1
	v_add_u32_e32 v64, v145, v151
	ds_read2_b64 v[64:67], v64 offset1:1
	v_lshl_add_u64 v[70:71], v[68:69], 0, v[126:127]
	s_waitcnt lgkmcnt(0)
	global_store_dwordx4 v[70:71], v[64:67], off
	s_nop 1
	v_add_u32_e32 v64, v145, v152
	ds_read2_b64 v[64:67], v64 offset1:1
	v_lshl_add_u64 v[70:71], v[68:69], 0, v[124:125]
	v_lshl_add_u64 v[68:69], v[68:69], 0, v[130:131]
	s_waitcnt lgkmcnt(0)
	global_store_dwordx4 v[70:71], v[64:67], off
	s_nop 1
	v_add_u32_e32 v64, v145, v154
	ds_read2_b64 v[64:67], v64 offset1:1
	s_waitcnt lgkmcnt(0)
	global_store_dwordx4 v[68:69], v[64:67], off
	s_waitcnt vmcnt(4)
	s_branch .LBB0_1191

.LBB0_1191:
	ds_write_b128 v218, v[80:83]
	ds_write_b128 v218, v[84:87] offset:16384
	ds_write_b128 v219, v[88:91]
	ds_write_b128 v219, v[92:95] offset:16384
	v_and_b32_e32 v69, 0xffff0000, v96
	v_and_b32_e32 v71, 0xffff0000, v97
	v_sub_f32_e32 v70, v229, v230
	v_add_f32_e32 v68, v70, v231
	v_sub_f32_e32 v68, v68, v135
	v_mul_f32_e32 v68, 0x3fb8aa3b, v68
	v_exp_f32_e32 v72, v68
	v_lshlrev_b32_e32 v68, 16, v96
	v_lshlrev_b32_e32 v70, 16, v97
	v_lshlrev_b32_e32 v74, 16, v99
	v_pk_mul_f32 v[68:69], v[72:73], v[68:69] op_sel_hi:[0,1]
	v_pk_mul_f32 v[70:71], v[72:73], v[70:71] op_sel_hi:[0,1]
	v_cvt_pk_bf16_f32 v68, v68, v69
	v_cvt_pk_bf16_f32 v69, v70, v71
	v_lshlrev_b32_e32 v70, 16, v98
	v_and_b32_e32 v71, 0xffff0000, v98
	v_and_b32_e32 v75, 0xffff0000, v99
	v_pk_mul_f32 v[70:71], v[72:73], v[70:71] op_sel_hi:[0,1]
	v_pk_mul_f32 v[72:73], v[72:73], v[74:75] op_sel_hi:[0,1]
	v_cvt_pk_bf16_f32 v70, v70, v71
	v_cvt_pk_bf16_f32 v71, v72, v73
	v_add_u32_e32 v72, 0, v169
	ds_write_b128 v72, v[96:99] offset:32768
	v_add_u32_e32 v64, s60, v169
	ds_write_b128 v64, v[68:71]
	v_and_b32_e32 v69, 0xffff0000, v100
	v_and_b32_e32 v71, 0xffff0000, v101
	v_sub_f32_e32 v70, v229, v232
	v_add_f32_e32 v68, v70, v233
	v_sub_f32_e32 v68, v68, v135
	v_mul_f32_e32 v68, 0x3fb8aa3b, v68
	v_exp_f32_e32 v72, v68
	v_lshlrev_b32_e32 v68, 16, v100
	v_lshlrev_b32_e32 v70, 16, v101
	v_lshlrev_b32_e32 v74, 16, v103
	v_pk_mul_f32 v[68:69], v[72:73], v[68:69] op_sel_hi:[0,1]
	v_pk_mul_f32 v[70:71], v[72:73], v[70:71] op_sel_hi:[0,1]
	v_cvt_pk_bf16_f32 v68, v68, v69
	v_cvt_pk_bf16_f32 v69, v70, v71
	v_lshlrev_b32_e32 v70, 16, v102
	v_and_b32_e32 v71, 0xffff0000, v102
	v_and_b32_e32 v75, 0xffff0000, v103
	v_pk_mul_f32 v[70:71], v[72:73], v[70:71] op_sel_hi:[0,1]
	v_pk_mul_f32 v[72:73], v[72:73], v[74:75] op_sel_hi:[0,1]
	v_cvt_pk_bf16_f32 v70, v70, v71
	v_cvt_pk_bf16_f32 v71, v72, v73
	v_add_u32_e32 v72, 0, v171
	ds_write_b128 v72, v[100:103] offset:32768
	v_add_u32_e32 v64, s60, v171
	ds_write_b128 v64, v[68:71]
	v_and_b32_e32 v69, 0xffff0000, v104
	v_and_b32_e32 v71, 0xffff0000, v105
	v_sub_f32_e32 v70, v229, v234
	v_add_f32_e32 v68, v70, v235
	v_sub_f32_e32 v68, v68, v135
	v_mul_f32_e32 v68, 0x3fb8aa3b, v68
	v_exp_f32_e32 v72, v68
	v_lshlrev_b32_e32 v68, 16, v104
	v_lshlrev_b32_e32 v70, 16, v105
	v_lshlrev_b32_e32 v74, 16, v107
	v_pk_mul_f32 v[68:69], v[72:73], v[68:69] op_sel_hi:[0,1]
	v_pk_mul_f32 v[70:71], v[72:73], v[70:71] op_sel_hi:[0,1]
	v_cvt_pk_bf16_f32 v68, v68, v69
	v_cvt_pk_bf16_f32 v69, v70, v71
	v_lshlrev_b32_e32 v70, 16, v106
	v_and_b32_e32 v71, 0xffff0000, v106
	v_and_b32_e32 v75, 0xffff0000, v107
	v_pk_mul_f32 v[70:71], v[72:73], v[70:71] op_sel_hi:[0,1]
	v_pk_mul_f32 v[72:73], v[72:73], v[74:75] op_sel_hi:[0,1]
	v_cvt_pk_bf16_f32 v70, v70, v71
	v_cvt_pk_bf16_f32 v71, v72, v73
	v_add_u32_e32 v72, 0, v173
	ds_write_b128 v72, v[104:107] offset:32768
	v_add_u32_e32 v64, s60, v173
	ds_write_b128 v64, v[68:71]
	v_and_b32_e32 v69, 0xffff0000, v108
	v_and_b32_e32 v71, 0xffff0000, v109
	v_sub_f32_e32 v70, v229, v236
	v_add_f32_e32 v68, v70, v237
	v_sub_f32_e32 v68, v68, v135
	v_mul_f32_e32 v68, 0x3fb8aa3b, v68
	v_exp_f32_e32 v72, v68
	v_lshlrev_b32_e32 v68, 16, v108
	v_lshlrev_b32_e32 v70, 16, v109
	v_lshlrev_b32_e32 v74, 16, v111
	v_pk_mul_f32 v[68:69], v[72:73], v[68:69] op_sel_hi:[0,1]
	v_pk_mul_f32 v[70:71], v[72:73], v[70:71] op_sel_hi:[0,1]
	v_cvt_pk_bf16_f32 v68, v68, v69
	v_cvt_pk_bf16_f32 v69, v70, v71
	v_lshlrev_b32_e32 v70, 16, v110
	v_and_b32_e32 v71, 0xffff0000, v110
	v_and_b32_e32 v75, 0xffff0000, v111
	v_pk_mul_f32 v[70:71], v[72:73], v[70:71] op_sel_hi:[0,1]
	v_pk_mul_f32 v[72:73], v[72:73], v[74:75] op_sel_hi:[0,1]
	v_cvt_pk_bf16_f32 v70, v70, v71
	v_cvt_pk_bf16_f32 v71, v72, v73
	v_add_u32_e32 v72, 0, v175
	ds_write_b128 v72, v[108:111] offset:32768
	v_add_u32_e32 v64, s60, v175
	ds_write_b128 v64, v[68:71]
	s_and_saveexec_b64 s[92:93], s[2:3]
	s_cbranch_execz .LBB0_1193
	ds_write_b32 v155, v238
	ds_write_b32 v156, v239
	v_max_f32_e32 v65, v134, v134
	v_max_f32_e32 v64, v240, v240
	v_max_f32_e32 v64, v65, v64
	v_add_f32_e32 v64, v238, v64
	ds_write_b32 v157, v64
	v_sub_f32_e32 v64, v229, v238
	v_add_f32_e32 v64, v64, v239
	v_sub_f32_e32 v64, v64, v135
	v_mul_f32_e32 v64, 0x3fb8aa3b, v64
	v_exp_f32_e32 v64, v64
	s_nop 0
	ds_write_b32 v158, v64
